# v21 + SB tile loop: 16 causal-diagonal fix-up blocks moved out of line (fall-through on off-diagonal tiles), their v_cmp masks computed only on the diagonal
# speedup vs baseline: 1.0023x; 1.0015x over previous
.Lsbd_668:
	s_or_b64 s[4:5], s[44:45], s[46:47]
	v_cndmask_b32_e64 v44, 0, v44, s[4:5]
	s_or_b64 s[4:5], vcc, s[42:43]
	v_cndmask_b32_e64 v45, 0, v45, s[44:45]
	v_cndmask_b32_e64 v82, 0, v82, s[4:5]
	s_mov_b32 s4, 0x3e0293ee
	v_cndmask_b32_e32 v83, 0, v83, vcc
	s_branch .LBB0_669
.Lsbd_670:
	v_cmp_lt_i32_e64 s[50:51], 2, v201
	v_cmp_lt_i32_e64 s[48:49], 3, v201
	v_cmp_lt_i32_e64 s[46:47], 34, v201
	v_cmp_lt_i32_e64 s[44:45], 35, v201
	s_or_b64 vcc, s[48:49], s[50:51]
	v_cndmask_b32_e32 v164, 0, v164, vcc
	s_or_b64 vcc, s[44:45], s[46:47]
	v_cndmask_b32_e64 v165, 0, v165, s[48:49]
	v_cndmask_b32_e32 v166, 0, v166, vcc
	v_cndmask_b32_e64 v167, 0, v167, s[44:45]
	s_branch .LBB0_671
.Lsbd_672:
	v_cmp_lt_i32_e64 s[50:51], 8, v201
	v_cmp_lt_i32_e64 s[48:49], 9, v201
	v_cmp_lt_i32_e64 s[46:47], 40, v201
	v_cmp_lt_i32_e64 s[44:45], 41, v201
	s_or_b64 vcc, s[48:49], s[50:51]
	v_cndmask_b32_e32 v98, 0, v98, vcc
	s_or_b64 vcc, s[44:45], s[46:47]
	v_cndmask_b32_e64 v99, 0, v99, s[48:49]
	v_cndmask_b32_e32 v100, 0, v100, vcc
	v_cndmask_b32_e64 v101, 0, v101, s[44:45]
	s_branch .LBB0_673
.Lsbd_674:
	v_cmp_lt_i32_e64 s[50:51], 10, v201
	v_cmp_lt_i32_e64 s[48:49], 11, v201
	v_cmp_lt_i32_e64 s[46:47], 42, v201
	v_cmp_lt_i32_e64 s[44:45], 43, v201
	s_or_b64 vcc, s[48:49], s[50:51]
	v_cndmask_b32_e32 v168, 0, v168, vcc
	s_or_b64 vcc, s[44:45], s[46:47]
	v_cndmask_b32_e64 v169, 0, v169, s[48:49]
	v_cndmask_b32_e32 v170, 0, v170, vcc
	v_cndmask_b32_e64 v171, 0, v171, s[44:45]
	s_branch .LBB0_675
.Lsbd_676:
	v_cmp_lt_i32_e64 s[50:51], 16, v201
	v_cmp_lt_i32_e64 s[48:49], 17, v201
	v_cmp_lt_i32_e64 s[46:47], 48, v201
	v_cmp_lt_i32_e64 s[44:45], 49, v201
	s_or_b64 vcc, s[48:49], s[50:51]
	v_cndmask_b32_e32 v104, 0, v104, vcc
	s_or_b64 vcc, s[44:45], s[46:47]
	v_cndmask_b32_e64 v105, 0, v105, s[48:49]
	v_cndmask_b32_e32 v106, 0, v106, vcc
	v_cndmask_b32_e64 v107, 0, v107, s[44:45]
	s_branch .LBB0_677
.Lsbd_678:
	v_cmp_lt_i32_e64 s[50:51], 18, v201
	v_cmp_lt_i32_e64 s[48:49], 19, v201
	v_cmp_lt_i32_e64 s[46:47], 50, v201
	v_cmp_lt_i32_e64 s[44:45], 51, v201
	s_or_b64 vcc, s[48:49], s[50:51]
	v_cndmask_b32_e32 v176, 0, v176, vcc
	s_or_b64 vcc, s[44:45], s[46:47]
	v_cndmask_b32_e64 v177, 0, v177, s[48:49]
	v_cndmask_b32_e32 v178, 0, v178, vcc
	v_cndmask_b32_e64 v179, 0, v179, s[44:45]
	s_branch .LBB0_679
.Lsbd_680:
	v_cmp_lt_i32_e64 s[50:51], 24, v201
	v_cmp_lt_i32_e64 s[48:49], 25, v201
	v_cmp_lt_i32_e64 s[46:47], 56, v201
	v_cmp_lt_i32_e64 s[44:45], 57, v201
	s_or_b64 vcc, s[48:49], s[50:51]
	v_cndmask_b32_e32 v172, 0, v172, vcc
	s_or_b64 vcc, s[44:45], s[46:47]
	v_cndmask_b32_e64 v173, 0, v173, s[48:49]
	v_cndmask_b32_e32 v174, 0, v174, vcc
	v_cndmask_b32_e64 v175, 0, v175, s[44:45]
	s_branch .LBB0_681
.Lsbd_682:
	v_cmp_lt_i32_e64 s[50:51], 26, v201
	v_cmp_lt_i32_e64 s[48:49], 27, v201
	v_cmp_lt_i32_e64 s[46:47], 58, v201
	v_cmp_lt_i32_e64 s[44:45], 59, v201
	s_or_b64 vcc, s[48:49], s[50:51]
	v_cndmask_b32_e32 v112, 0, v112, vcc
	s_or_b64 vcc, s[44:45], s[46:47]
	v_cndmask_b32_e64 v113, 0, v113, s[48:49]
	v_cndmask_b32_e32 v184, 0, v184, vcc
	v_cndmask_b32_e64 v185, 0, v185, s[44:45]
	s_branch .LBB0_683
.Lsbd_684:
	v_cmp_lt_i32_e32 vcc, 0, v201
	s_nop 1
	v_cndmask_b32_e32 v45, 0, v45, vcc
	v_cmp_lt_i32_e32 vcc, 1, v201
	s_nop 1
	v_cndmask_b32_e32 v204, 0, v204, vcc
	v_cmp_lt_i32_e32 vcc, 32, v201
	s_nop 1
	v_cndmask_b32_e32 v34, 0, v34, vcc
	v_cmp_lt_i32_e32 vcc, 33, v201
	s_nop 1
	v_cndmask_b32_e32 v44, 0, v44, vcc
	s_branch .LBB0_685
.Lsbd_686:
	v_cmp_lt_i32_e32 vcc, 2, v201
	s_nop 1
	v_cndmask_b32_e32 v42, 0, v42, vcc
	v_cmp_lt_i32_e32 vcc, 3, v201
	s_nop 1
	v_cndmask_b32_e32 v43, 0, v43, vcc
	v_cmp_lt_i32_e32 vcc, 34, v201
	s_nop 1
	v_cndmask_b32_e32 v40, 0, v40, vcc
	v_cmp_lt_i32_e32 vcc, 35, v201
	s_nop 1
	v_cndmask_b32_e32 v41, 0, v41, vcc
	s_branch .LBB0_687
.Lsbd_688:
	v_cmp_lt_i32_e32 vcc, 8, v201
	s_nop 1
	v_cndmask_b32_e32 v98, 0, v98, vcc
	v_cmp_lt_i32_e32 vcc, 9, v201
	s_nop 1
	v_cndmask_b32_e32 v99, 0, v99, vcc
	v_cmp_lt_i32_e32 vcc, 40, v201
	s_nop 1
	v_cndmask_b32_e32 v46, 0, v46, vcc
	v_cmp_lt_i32_e32 vcc, 41, v201
	s_nop 1
	v_cndmask_b32_e32 v47, 0, v47, vcc
	s_branch .LBB0_689
.Lsbd_690:
	v_cmp_lt_i32_e32 vcc, 10, v201
	s_nop 1
	v_cndmask_b32_e32 v86, 0, v86, vcc
	v_cmp_lt_i32_e32 vcc, 11, v201
	s_nop 1
	v_cndmask_b32_e32 v87, 0, v87, vcc
	v_cmp_lt_i32_e32 vcc, 42, v201
	s_nop 1
	v_cndmask_b32_e32 v48, 0, v48, vcc
	v_cmp_lt_i32_e32 vcc, 43, v201
	s_nop 1
	v_cndmask_b32_e32 v49, 0, v49, vcc
	s_branch .LBB0_691
.Lsbd_692:
	v_cmp_lt_i32_e32 vcc, 16, v201
	s_nop 1
	v_cndmask_b32_e32 v90, 0, v90, vcc
	v_cmp_lt_i32_e32 vcc, 17, v201
	s_nop 1
	v_cndmask_b32_e32 v91, 0, v91, vcc
	v_cmp_lt_i32_e32 vcc, 48, v201
	s_nop 1
	v_cndmask_b32_e32 v84, 0, v84, vcc
	v_cmp_lt_i32_e32 vcc, 49, v201
	s_nop 1
	v_cndmask_b32_e32 v85, 0, v85, vcc
	s_branch .LBB0_693
.Lsbd_694:
	v_cmp_lt_i32_e32 vcc, 18, v201
	s_nop 1
	v_cndmask_b32_e32 v92, 0, v92, vcc
	v_cmp_lt_i32_e32 vcc, 19, v201
	s_nop 1
	v_cndmask_b32_e32 v93, 0, v93, vcc
	v_cmp_lt_i32_e32 vcc, 50, v201
	s_nop 1
	v_cndmask_b32_e32 v88, 0, v88, vcc
	v_cmp_lt_i32_e32 vcc, 51, v201
	s_nop 1
	v_cndmask_b32_e32 v89, 0, v89, vcc
	s_branch .LBB0_695
.Lsbd_696:
	v_cmp_lt_i32_e32 vcc, 24, v201
	s_nop 1
	v_cndmask_b32_e32 v100, 0, v100, vcc
	v_cmp_lt_i32_e32 vcc, 25, v201
	s_nop 1
	v_cndmask_b32_e32 v101, 0, v101, vcc
	v_cmp_lt_i32_e32 vcc, 56, v201
	s_nop 1
	v_cndmask_b32_e32 v94, 0, v94, vcc
	v_cmp_lt_i32_e32 vcc, 57, v201
	s_nop 1
	v_cndmask_b32_e32 v95, 0, v95, vcc
	s_branch .LBB0_697
.Lsbd_698:
	v_cmp_lt_i32_e32 vcc, 26, v201
	s_nop 1
	v_cndmask_b32_e32 v102, 0, v102, vcc
	v_cmp_lt_i32_e32 vcc, 27, v201
	s_nop 1
	v_cndmask_b32_e32 v103, 0, v103, vcc
	v_cmp_lt_i32_e32 vcc, 58, v201
	s_nop 1
	v_cndmask_b32_e32 v96, 0, v96, vcc
	v_cmp_lt_i32_e32 vcc, 59, v201
	s_nop 1
	v_cndmask_b32_e32 v97, 0, v97, vcc
	s_branch .LBB0_699

.LBB0_667:
	s_lshl_b32 s53, s21, 14
	v_add_u32_e32 v34, s53, v191
	v_add_u32_e32 v40, v34, v192
	ds_read_b128 v[36:39], v40 offset:32768
	s_mov_b32 s4, 0x3e0293ee
	s_cmp_ge_i32 s34, s9
	s_cselect_b64 s[48:49], -1, 0
	s_cmp_lt_i32 s34, s9
	v_cmp_lt_i32_e64 s[46:47], 0, v201
	v_cmp_lt_i32_e64 s[44:45], 1, v201
	v_cmp_lt_i32_e64 s[42:43], 32, v201
	v_cmp_lt_i32_e32 vcc, 33, v201
	s_waitcnt vmcnt(7) lgkmcnt(0)
	v_mfma_f32_32x32x16_bf16 v[82:97], v[36:39], v[122:125], 0
	ds_read_b128 v[36:39], v40 offset:40960
	v_add_u32_e32 v40, v34, v193
	s_waitcnt lgkmcnt(0)
	v_mfma_f32_32x32x16_bf16 v[98:113], v[36:39], v[122:125], 0
	ds_read_b128 v[36:39], v40 offset:32768
	s_waitcnt vmcnt(6) lgkmcnt(0)
	v_mfma_f32_32x32x16_bf16 v[82:97], v[36:39], v[126:129], v[82:97]
	ds_read_b128 v[36:39], v40 offset:40960
	v_add_u32_e32 v40, v34, v194
	s_waitcnt lgkmcnt(0)
	v_mfma_f32_32x32x16_bf16 v[98:113], v[36:39], v[126:129], v[98:113]
	ds_read_b128 v[36:39], v40 offset:32768
	s_waitcnt vmcnt(5) lgkmcnt(0)
	v_mfma_f32_32x32x16_bf16 v[82:97], v[36:39], v[130:133], v[82:97]
	ds_read_b128 v[36:39], v40 offset:40960
	v_add_u32_e32 v40, v34, v195
	s_waitcnt lgkmcnt(0)
	v_mfma_f32_32x32x16_bf16 v[98:113], v[36:39], v[130:133], v[98:113]
	ds_read_b128 v[36:39], v40 offset:32768
	s_waitcnt vmcnt(4) lgkmcnt(0)
	v_mfma_f32_32x32x16_bf16 v[82:97], v[36:39], v[134:137], v[82:97]
	ds_read_b128 v[36:39], v40 offset:40960
	v_add_u32_e32 v40, v34, v196
	s_waitcnt lgkmcnt(0)
	v_mfma_f32_32x32x16_bf16 v[98:113], v[36:39], v[134:137], v[98:113]
	ds_read_b128 v[36:39], v40 offset:32768
	s_waitcnt vmcnt(3) lgkmcnt(0)
	v_mfma_f32_32x32x16_bf16 v[82:97], v[36:39], v[138:141], v[82:97]
	ds_read_b128 v[36:39], v40 offset:40960
	v_add_u32_e32 v40, v34, v197
	s_waitcnt lgkmcnt(0)
	v_mfma_f32_32x32x16_bf16 v[98:113], v[36:39], v[138:141], v[98:113]
	ds_read_b128 v[36:39], v40 offset:32768
	s_waitcnt vmcnt(2) lgkmcnt(0)
	v_mfma_f32_32x32x16_bf16 v[82:97], v[36:39], v[142:145], v[82:97]
	ds_read_b128 v[36:39], v40 offset:40960
	v_add_u32_e32 v40, v34, v198
	v_add_u32_e32 v34, v34, v199
	s_waitcnt lgkmcnt(0)
	v_mfma_f32_32x32x16_bf16 v[98:113], v[36:39], v[142:145], v[98:113]
	ds_read_b128 v[36:39], v40 offset:32768
	s_waitcnt vmcnt(1) lgkmcnt(0)
	v_mfma_f32_32x32x16_bf16 v[82:97], v[36:39], v[146:149], v[82:97]
	ds_read_b128 v[36:39], v40 offset:40960
	ds_read_b128 v[40:43], v34 offset:40960
	s_waitcnt lgkmcnt(1)
	v_mfma_f32_32x32x16_bf16 v[98:113], v[36:39], v[146:149], v[98:113]
	ds_read_b128 v[36:39], v34 offset:32768
	s_waitcnt vmcnt(0) lgkmcnt(0)
	v_mfma_f32_32x32x16_bf16 v[82:97], v[36:39], v[154:157], v[82:97]
	v_mfma_f32_32x32x16_bf16 v[98:113], v[40:43], v[154:157], v[98:113]
	s_nop 10
	v_mul_f32_e64 v38, v82, s4
	v_mul_f32_e64 v39, v83, s4
	v_exp_f32_e64 v40, -|v38|
	v_exp_f32_e64 v41, -|v39|
	v_max_f32_e32 v44, 0, v38
	v_max_f32_e32 v45, 0, v39
	v_pk_mul_f32 v[36:37], v[98:99], s[4:5] op_sel_hi:[1,0]
	s_nop 0
	v_exp_f32_e64 v42, -|v36|
	v_exp_f32_e64 v43, -|v37|
	v_pk_add_f32 v[40:41], v[40:41], 1.0 op_sel_hi:[1,0]
	v_pk_add_f32 v[42:43], v[42:43], 1.0 op_sel_hi:[1,0]
	v_log_f32_e32 v40, v40
	v_log_f32_e32 v41, v41
	v_log_f32_e32 v42, v42
	v_log_f32_e32 v43, v43
	v_pk_add_f32 v[44:45], v[44:45], v[40:41]
	v_max_f32_e32 v40, 0, v36
	v_max_f32_e32 v41, 0, v37
	v_pk_add_f32 v[82:83], v[40:41], v[42:43]
	s_cbranch_scc0 .Lsbd_668
.LBB0_669:
	v_pk_mul_f32 v[40:41], v[84:85], s[4:5] op_sel_hi:[1,0]
	v_pk_mul_f32 v[42:43], v[100:101], s[4:5] op_sel_hi:[1,0]
	v_exp_f32_e64 v46, -|v40|
	v_exp_f32_e64 v47, -|v41|
	v_exp_f32_e64 v48, -|v42|
	v_exp_f32_e64 v49, -|v43|
	v_max_f32_e32 v84, 0, v40
	v_pk_add_f32 v[46:47], v[46:47], 1.0 op_sel_hi:[1,0]
	v_max_f32_e32 v85, 0, v41
	v_pk_add_f32 v[48:49], v[48:49], 1.0 op_sel_hi:[1,0]
	v_log_f32_e32 v46, v46
	v_log_f32_e32 v47, v47
	v_log_f32_e32 v48, v48
	v_log_f32_e32 v49, v49
	v_cndmask_b32_e64 v34, 0, 1, s[48:49]
	v_pk_add_f32 v[164:165], v[84:85], v[46:47]
	v_max_f32_e32 v46, 0, v42
	v_max_f32_e32 v47, 0, v43
	v_pk_add_f32 v[166:167], v[46:47], v[48:49]
	v_cmp_ne_u32_e64 s[42:43], 1, v34
	s_andn2_b64 vcc, exec, s[48:49]
	s_cbranch_vccz .Lsbd_670
.LBB0_671:
	v_pk_mul_f32 v[46:47], v[86:87], s[4:5] op_sel_hi:[1,0]
	v_pk_mul_f32 v[48:49], v[102:103], s[4:5] op_sel_hi:[1,0]
	v_exp_f32_e64 v84, -|v46|
	v_exp_f32_e64 v85, -|v47|
	v_exp_f32_e64 v86, -|v48|
	v_exp_f32_e64 v87, -|v49|
	v_max_f32_e32 v98, 0, v46
	v_pk_add_f32 v[84:85], v[84:85], 1.0 op_sel_hi:[1,0]
	v_max_f32_e32 v99, 0, v47
	v_pk_add_f32 v[86:87], v[86:87], 1.0 op_sel_hi:[1,0]
	v_log_f32_e32 v84, v84
	v_log_f32_e32 v85, v85
	v_log_f32_e32 v86, v86
	v_log_f32_e32 v87, v87
	s_and_b64 vcc, exec, s[42:43]
	v_pk_add_f32 v[98:99], v[98:99], v[84:85]
	v_max_f32_e32 v84, 0, v48
	v_max_f32_e32 v85, 0, v49
	v_pk_add_f32 v[100:101], v[84:85], v[86:87]
	s_cbranch_vccz .Lsbd_672
.LBB0_673:
	v_pk_mul_f32 v[84:85], v[88:89], s[4:5] op_sel_hi:[1,0]
	v_pk_mul_f32 v[86:87], v[104:105], s[4:5] op_sel_hi:[1,0]
	v_exp_f32_e64 v88, -|v84|
	v_exp_f32_e64 v89, -|v85|
	v_exp_f32_e64 v102, -|v86|
	v_exp_f32_e64 v103, -|v87|
	v_max_f32_e32 v104, 0, v84
	v_pk_add_f32 v[88:89], v[88:89], 1.0 op_sel_hi:[1,0]
	v_max_f32_e32 v105, 0, v85
	v_pk_add_f32 v[102:103], v[102:103], 1.0 op_sel_hi:[1,0]
	v_log_f32_e32 v88, v88
	v_log_f32_e32 v89, v89
	v_log_f32_e32 v102, v102
	v_log_f32_e32 v103, v103
	s_and_b64 vcc, exec, s[42:43]
	v_pk_add_f32 v[168:169], v[104:105], v[88:89]
	v_max_f32_e32 v88, 0, v86
	v_max_f32_e32 v89, 0, v87
	v_pk_add_f32 v[170:171], v[88:89], v[102:103]
	s_cbranch_vccz .Lsbd_674
.LBB0_675:
	v_pk_mul_f32 v[88:89], v[90:91], s[4:5] op_sel_hi:[1,0]
	v_pk_mul_f32 v[90:91], v[106:107], s[4:5] op_sel_hi:[1,0]
	v_exp_f32_e64 v102, -|v88|
	v_exp_f32_e64 v103, -|v89|
	v_exp_f32_e64 v104, -|v90|
	v_exp_f32_e64 v105, -|v91|
	v_max_f32_e32 v106, 0, v88
	v_pk_add_f32 v[102:103], v[102:103], 1.0 op_sel_hi:[1,0]
	v_max_f32_e32 v107, 0, v89
	v_pk_add_f32 v[104:105], v[104:105], 1.0 op_sel_hi:[1,0]
	v_log_f32_e32 v102, v102
	v_log_f32_e32 v103, v103
	v_log_f32_e32 v172, v104
	v_log_f32_e32 v173, v105
	s_and_b64 vcc, exec, s[42:43]
	v_pk_add_f32 v[104:105], v[106:107], v[102:103]
	v_max_f32_e32 v102, 0, v90
	v_max_f32_e32 v103, 0, v91
	v_pk_add_f32 v[106:107], v[102:103], v[172:173]
	s_cbranch_vccz .Lsbd_676
.LBB0_677:
	v_pk_mul_f32 v[92:93], v[92:93], s[4:5] op_sel_hi:[1,0]
	v_pk_mul_f32 v[102:103], v[108:109], s[4:5] op_sel_hi:[1,0]
	v_exp_f32_e64 v108, -|v92|
	v_exp_f32_e64 v109, -|v93|
	v_exp_f32_e64 v172, -|v102|
	v_exp_f32_e64 v173, -|v103|
	v_max_f32_e32 v174, 0, v92
	v_pk_add_f32 v[108:109], v[108:109], 1.0 op_sel_hi:[1,0]
	v_max_f32_e32 v175, 0, v93
	v_pk_add_f32 v[172:173], v[172:173], 1.0 op_sel_hi:[1,0]
	v_log_f32_e32 v108, v108
	v_log_f32_e32 v109, v109
	v_log_f32_e32 v172, v172
	v_log_f32_e32 v173, v173
	s_and_b64 vcc, exec, s[42:43]
	v_pk_add_f32 v[176:177], v[174:175], v[108:109]
	v_max_f32_e32 v108, 0, v102
	v_max_f32_e32 v109, 0, v103
	v_pk_add_f32 v[178:179], v[108:109], v[172:173]
	s_cbranch_vccz .Lsbd_678
.LBB0_679:
	v_pk_mul_f32 v[94:95], v[94:95], s[4:5] op_sel_hi:[1,0]
	v_pk_mul_f32 v[108:109], v[110:111], s[4:5] op_sel_hi:[1,0]
	v_exp_f32_e64 v110, -|v94|
	v_exp_f32_e64 v111, -|v95|
	v_exp_f32_e64 v172, -|v108|
	v_exp_f32_e64 v173, -|v109|
	v_max_f32_e32 v174, 0, v94
	v_pk_add_f32 v[110:111], v[110:111], 1.0 op_sel_hi:[1,0]
	v_max_f32_e32 v175, 0, v95
	v_pk_add_f32 v[172:173], v[172:173], 1.0 op_sel_hi:[1,0]
	v_log_f32_e32 v110, v110
	v_log_f32_e32 v111, v111
	v_log_f32_e32 v180, v172
	v_log_f32_e32 v181, v173
	s_and_b64 vcc, exec, s[42:43]
	v_pk_add_f32 v[172:173], v[174:175], v[110:111]
	v_max_f32_e32 v110, 0, v108
	v_max_f32_e32 v111, 0, v109
	v_pk_add_f32 v[174:175], v[110:111], v[180:181]
	s_cbranch_vccz .Lsbd_680
.LBB0_681:
	v_pk_mul_f32 v[96:97], v[96:97], s[4:5] op_sel_hi:[1,0]
	v_pk_mul_f32 v[110:111], v[112:113], s[4:5] op_sel_hi:[1,0]
	v_exp_f32_e64 v112, -|v96|
	v_exp_f32_e64 v113, -|v97|
	v_exp_f32_e64 v180, -|v110|
	v_exp_f32_e64 v181, -|v111|
	v_max_f32_e32 v182, 0, v96
	v_pk_add_f32 v[112:113], v[112:113], 1.0 op_sel_hi:[1,0]
	v_max_f32_e32 v183, 0, v97
	v_pk_add_f32 v[180:181], v[180:181], 1.0 op_sel_hi:[1,0]
	v_log_f32_e32 v112, v112
	v_log_f32_e32 v113, v113
	v_log_f32_e32 v180, v180
	v_log_f32_e32 v181, v181
	s_and_b64 vcc, exec, s[42:43]
	v_pk_add_f32 v[112:113], v[182:183], v[112:113]
	v_max_f32_e32 v182, 0, v110
	v_max_f32_e32 v183, 0, v111
	v_pk_add_f32 v[184:185], v[182:183], v[180:181]
	s_cbranch_vccz .Lsbd_682
.LBB0_683:
	v_sub_f32_e64 v34, -v175, v174
	v_sub_f32_e64 v180, -v185, v184
	v_add_f32_e32 v34, v34, v180
	v_mov_b32_e32 v180, v34
	s_nop 1
	v_permlane32_swap_b32_e32 v34, v180
	v_add_f32_e32 v203, v202, v180
	v_add_f32_e32 v207, v203, v34
	v_sub_f32_e64 v34, -v107, v106
	v_sub_f32_e64 v180, -v179, v178
	v_add_f32_e32 v34, v34, v180
	v_mov_b32_e32 v180, v34
	s_nop 1
	v_permlane32_swap_b32_e32 v34, v180
	v_pk_add_f32 v[182:183], v[170:171], 0 neg_lo:[1,1] neg_hi:[1,1]
	v_add_f32_e32 v208, v207, v180
	v_xor_b32_e32 v180, 0x80000000, v101
	v_mov_b32_e32 v181, v183
	v_mov_b32_e32 v182, v100
	v_mov_b32_e32 v183, v170
	v_pk_add_f32 v[180:181], v[180:181], v[182:183] neg_lo:[0,1] neg_hi:[0,1]
	v_add_f32_e32 v211, v208, v34
	v_pk_add_f32 v[180:181], v[180:181], v[180:181] op_sel:[0,1] op_sel_hi:[1,0]
	v_pk_add_f32 v[182:183], v[166:167], 0 neg_lo:[1,1] neg_hi:[1,1]
	v_mov_b32_e32 v34, v180
	s_nop 1
	v_permlane32_swap_b32_e32 v180, v34
	v_add_f32_e32 v212, v211, v34
	v_add_f32_e32 v34, v212, v180
	v_xor_b32_e32 v180, 0x80000000, v83
	v_mov_b32_e32 v181, v183
	v_mov_b32_e32 v182, v82
	v_mov_b32_e32 v183, v166
	v_pk_add_f32 v[180:181], v[180:181], v[182:183] neg_lo:[0,1] neg_hi:[0,1]
	v_pk_add_f32 v[182:183], v[168:169], 0 neg_lo:[1,1] neg_hi:[1,1]
	v_pk_add_f32 v[180:181], v[180:181], v[180:181] op_sel:[0,1] op_sel_hi:[1,0]
	v_mov_b32_e32 v182, v98
	v_mov_b32_e32 v181, v180
	s_nop 1
	v_permlane32_swap_b32_e32 v180, v181
	v_add_f32_e32 v181, v34, v181
	v_cndmask_b32_e64 v34, v34, v181, s[38:39]
	v_sub_f32_e32 v167, v34, v167
	v_sub_f32_e32 v166, v167, v166
	v_add_f32_e32 v205, v181, v180
	v_sub_f32_e32 v181, v166, v83
	v_sub_f32_e32 v180, v181, v82
	v_sub_f32_e64 v34, -v173, v172
	v_sub_f32_e64 v82, -v113, v112
	v_add_f32_e32 v34, v34, v82
	v_mov_b32_e32 v82, v34
	s_nop 1
	v_permlane32_swap_b32_e32 v34, v82
	v_add_f32_e32 v206, v205, v82
	v_add_f32_e32 v209, v206, v34
	v_sub_f32_e64 v34, -v105, v104
	v_sub_f32_e64 v82, -v177, v176
	v_add_f32_e32 v34, v34, v82
	v_mov_b32_e32 v82, v34
	s_nop 1
	v_permlane32_swap_b32_e32 v34, v82
	v_add_f32_e32 v210, v209, v82
	v_xor_b32_e32 v82, 0x80000000, v99
	v_mov_b32_e32 v83, v183
	v_mov_b32_e32 v183, v168
	v_pk_add_f32 v[82:83], v[82:83], v[182:183] neg_lo:[0,1] neg_hi:[0,1]
	v_add_f32_e32 v213, v210, v34
	v_pk_add_f32 v[82:83], v[82:83], v[82:83] op_sel:[0,1] op_sel_hi:[1,0]
	v_pk_add_f32 v[182:183], v[164:165], 0 neg_lo:[1,1] neg_hi:[1,1]
	v_mov_b32_e32 v34, v82
	s_nop 1
	v_permlane32_swap_b32_e32 v82, v34
	v_add_f32_e32 v223, v213, v34
	v_add_f32_e32 v34, v223, v82
	v_xor_b32_e32 v82, 0x80000000, v45
	v_mov_b32_e32 v83, v183
	v_mov_b32_e32 v182, v44
	v_mov_b32_e32 v183, v164
	v_pk_add_f32 v[82:83], v[82:83], v[182:183] neg_lo:[0,1] neg_hi:[0,1]
	v_pk_add_f32 v[36:37], v[36:37], v[180:181]
	v_pk_add_f32 v[82:83], v[82:83], v[82:83] op_sel:[0,1] op_sel_hi:[1,0]
	s_and_b64 vcc, exec, s[42:43]
	v_mov_b32_e32 v83, v82
	s_nop 1
	v_permlane32_swap_b32_e32 v82, v83
	v_add_f32_e32 v83, v34, v83
	v_cndmask_b32_e64 v34, v34, v83, s[38:39]
	v_sub_f32_e32 v165, v34, v165
	v_sub_f32_e32 v164, v165, v164
	v_sub_f32_e32 v45, v164, v45
	v_sub_f32_e32 v44, v45, v44
	v_pk_add_f32 v[38:39], v[38:39], v[44:45]
	v_exp_f32_e32 v34, v36
	v_exp_f32_e32 v45, v38
	v_exp_f32_e32 v204, v39
	v_exp_f32_e32 v44, v37
	s_cbranch_vccz .Lsbd_684
.LBB0_685:
	v_pk_add_f32 v[36:37], v[40:41], v[164:165]
	v_pk_add_f32 v[38:39], v[42:43], v[166:167]
	v_exp_f32_e32 v42, v36
	v_exp_f32_e32 v43, v37
	v_exp_f32_e32 v40, v38
	v_exp_f32_e32 v41, v39
	s_and_b64 vcc, exec, s[42:43]
	s_cbranch_vccz .Lsbd_686
.LBB0_687:
	v_cndmask_b32_e64 v36, v211, v212, s[38:39]
	v_cndmask_b32_e64 v38, v213, v223, s[38:39]
	v_sub_f32_e32 v37, v36, v171
	v_sub_f32_e32 v39, v38, v169
	v_sub_f32_e32 v36, v37, v170
	v_sub_f32_e32 v38, v39, v168
	v_sub_f32_e32 v101, v36, v101
	v_sub_f32_e32 v99, v38, v99
	v_sub_f32_e32 v100, v101, v100
	v_sub_f32_e32 v98, v99, v98
	v_pk_add_f32 v[46:47], v[46:47], v[98:99]
	v_pk_add_f32 v[48:49], v[48:49], v[100:101]
	v_exp_f32_e32 v98, v46
	v_exp_f32_e32 v99, v47
	v_exp_f32_e32 v46, v48
	v_exp_f32_e32 v47, v49
	s_and_b64 vcc, exec, s[42:43]
	s_cbranch_vccz .Lsbd_688
.LBB0_689:
	v_pk_add_f32 v[38:39], v[84:85], v[38:39]
	v_pk_add_f32 v[36:37], v[86:87], v[36:37]
	v_exp_f32_e32 v86, v38
	v_exp_f32_e32 v87, v39
	v_exp_f32_e32 v48, v36
	v_exp_f32_e32 v49, v37
	s_and_b64 vcc, exec, s[42:43]
	s_cbranch_vccz .Lsbd_690
.LBB0_691:
	v_cndmask_b32_e64 v36, v207, v208, s[38:39]
	v_cndmask_b32_e64 v38, v209, v210, s[38:39]
	v_sub_f32_e32 v37, v36, v179
	v_sub_f32_e32 v39, v38, v177
	v_sub_f32_e32 v36, v37, v178
	v_sub_f32_e32 v38, v39, v176
	v_sub_f32_e32 v85, v36, v107
	v_sub_f32_e32 v101, v38, v105
	v_sub_f32_e32 v84, v85, v106
	v_sub_f32_e32 v100, v101, v104
	v_pk_add_f32 v[88:89], v[88:89], v[100:101]
	v_pk_add_f32 v[84:85], v[90:91], v[84:85]
	v_exp_f32_e32 v90, v88
	v_exp_f32_e32 v91, v89
	v_exp_f32_e32 v84, v84
	v_exp_f32_e32 v85, v85
	s_and_b64 vcc, exec, s[42:43]
	s_cbranch_vccz .Lsbd_692
.LBB0_693:
	v_pk_add_f32 v[38:39], v[92:93], v[38:39]
	v_pk_add_f32 v[36:37], v[102:103], v[36:37]
	v_exp_f32_e32 v92, v38
	v_exp_f32_e32 v93, v39
	v_exp_f32_e32 v88, v36
	v_exp_f32_e32 v89, v37
	s_and_b64 vcc, exec, s[42:43]
	s_cbranch_vccz .Lsbd_694
.LBB0_695:
	v_cndmask_b32_e64 v36, v202, v203, s[38:39]
	v_cndmask_b32_e64 v38, v205, v206, s[38:39]
	v_sub_f32_e32 v37, v36, v185
	v_sub_f32_e32 v39, v38, v113
	v_sub_f32_e32 v36, v37, v184
	v_sub_f32_e32 v38, v39, v112
	v_sub_f32_e32 v101, v36, v175
	v_sub_f32_e32 v103, v38, v173
	v_sub_f32_e32 v100, v101, v174
	v_sub_f32_e32 v102, v103, v172
	v_pk_add_f32 v[94:95], v[94:95], v[102:103]
	v_pk_add_f32 v[102:103], v[108:109], v[100:101]
	v_exp_f32_e32 v100, v94
	v_exp_f32_e32 v101, v95
	v_exp_f32_e32 v94, v102
	v_exp_f32_e32 v95, v103
	s_and_b64 vcc, exec, s[42:43]
	s_cbranch_vccz .Lsbd_696
.LBB0_697:
	v_pk_add_f32 v[38:39], v[96:97], v[38:39]
	v_pk_add_f32 v[36:37], v[110:111], v[36:37]
	v_exp_f32_e32 v102, v38
	v_exp_f32_e32 v103, v39
	v_exp_f32_e32 v96, v36
	v_exp_f32_e32 v97, v37
	s_and_b64 vcc, exec, s[42:43]
	s_cbranch_vccz .Lsbd_698
